# + m21: the sync-only barriers (after W_a/W_b and batch-0 W_out) are XCD-local: no cross-XCD arrival/wait; next full barrier re-synchronises; guarded by the run-time placement check
# speedup vs baseline: 1.0035x; 1.0035x over previous
; __device__ __forceinline__ unsigned xb_ld(unsigned* p)              { return __hip_atomic_load(p, __ATOMIC_RELAXED, __HIP_MEMORY_SCOPE_AGENT); }
; __device__ __forceinline__ unsigned xb_add(unsigned* p, unsigned v) { return __hip_atomic_fetch_add(p, v, __ATOMIC_RELAXED, __HIP_MEMORY_SCOPE_AGENT); }
; #define XB_SPIN(cond, bar) do { unsigned _sp = 0; while (cond) { __builtin_amdgcn_s_sleep(0); \
;     if ((++_sp & 255u) == 0u) { if (xb_ld(&(bar)[XB_TMO])) break; if (_sp > XB_SPIN_CAP) { atomicAdd(&(bar)[XB_TMO], 1u); break; } } } } while (0)
; __device__ __forceinline__ void xcd_barrier(const XcdBarrier& b) {
;     ...
;         const unsigned old = xb_add(&bar[XB_XSUB(b.x)], 1u);
;         const unsigned gen = old / nloc;
;         if (old + 1u == (gen + 1u) * nloc) {
;             __builtin_amdgcn_fence(__ATOMIC_RELEASE, "agent");
;             asm volatile("s_waitcnt vmcnt(0)" ::: "memory");
;             const unsigned og = xb_add(&bar[XB_TOP], 1u);
;             const unsigned tg = og / nx;
;             if (og + 1u == (tg + 1u) * nx) xb_add(&bar[XB_TOPGEN], 1u);
;             else XB_SPIN(xb_ld(&bar[XB_TOPGEN]) == tg, bar);
;             __builtin_amdgcn_fence(__ATOMIC_ACQUIRE, "agent");
;             xb_add(&bar[XB_XGEN(b.x)], 1u);
;             asm volatile("s_waitcnt vmcnt(0)" ::: "memory");
.Lfull_l:
	buffer_wbl2 sc1
	buffer_inv sc1
	s_branch .Lnf_l2
.Lnf_l:
	s_waitcnt lgkmcnt(0)
	s_branch .LBB0_773
